# attention loop: one workgroup barrier per half-step (V tile written at the start of the next half-step from held registers) + QK VALU redistribution; barrier v3; sc1 stores
# speedup vs baseline: 1.0062x; 1.0062x over previous
; #define SBAR() __builtin_amdgcn_sched_barrier(0)
; __device__ __forceinline__ int v_st(int k, int c) { const int kk = (k & ~0xC) | ((k & 4) << 1) | ((k & 8) >> 1); return ((kk >> 3) * 4 + (c >> 5)) * 512 + ((kk & 7) * 32 + (c & 31)) * 2; }
; __device__ __forceinline__ int v_rd_base(int lane) { return ((lane & 3) << 3) | (((lane >> 2) & 3) << 6) | (((lane >> 4) & 1) << 5) | (((lane >> 5) & 1) << 8); }
; #define VMW() asm volatile("s_waitcnt vmcnt(0)" ::: "memory")
; #define SLOAD_H(Kp, Vp, k0) do { S.st_v0 = load8(ROW(Vp, k0, sr)); S.st_v1 = load8(ROW(Vp, k0, 32 + sr));              \
;                          S.st_k0 = load8(ROW(Kp, k0, sr)); S.st_k1 = load8(ROW(Kp, k0, 32 + sr)); } while (0)
; #define SWRITE_HV(bf) do { *(bf16x8*)(V_lds + (bf) * SHM_V + vst0) = S.st_v0; *(bf16x8*)(V_lds + (bf) * SHM_V + vst1) = S.st_v1; } while (0)
; #define SWRITE_H(bf) do { SWRITE_HV(bf); SWRITE_HK(bf); } while (0)
; #define MASKT(P0_, P1_, t) do { const int kb_ = KBASE(t); if (kb_ + KVBLK - 1 > qlo) mask_tile(P0_, P1_, qm - kb_, (unsigned)W); } while (0)
; __device__ __forceinline__ void moba_block(const BlockRef& cur, const BlockRef& nxt, char* lds, Seam& S) {
;     ...
;     float m_reg = -1e30f, l_reg = 0; f32x16 o[4] = {};
;     const int sr = tid >> 4, sc = (tid & 15) * 8, vst0 = v_st(sr, sc), vst1 = v_st(32 + sr, sc), kws = KSWZ(sr, sc * 2);
;     const int vb0 = (int)(uintptr_t)V_lds + v_rd_base(lane);
;     const bf16* Kh = cur.K; const bf16* Vh = cur.V;
;     const int qb = cur.qb;
;     const unsigned sel = gate_select(S.qr, lds, qb, r32, hi);
;     ...
;     constexpr int NQL = 8;
;     ...
;     f32x16 pA0, pA1, pB0, pB1; float mnA, mnB, alA, alB; bf16x8 pa0, pa1, pa2, pa3;
;     SWRITE_HV(0); SBAR();
;     if (NT > 1) { SLOAD_H(Kh, Vh, KBASE(1)); }
;     SBAR(); qkt<0>(pA0, pA1, K_lds, r32, hi, S.qr);
;     MASKT(pA0, pA1, 0); partialSM(pA0, pA1, m_reg, mnA, alA, RSEL(0));
;     if (NT > 1) { VMW(); SWRITE_H(1); }
;     __syncthreads();
.LBB0_88:
	s_and_b32 s0, s3, 0x3fffffc0
	v_and_b32_e32 v51, 63, v183
	s_lshl_b32 s0, s0, 2
	s_lshl_b32 s2, s44, 2
	s_add_i32 s0, s0, 0
	v_lshlrev_b32_e32 v52, 8, v166
	v_and_b32_e32 v53, 0x70, v183
	v_lshlrev_b32_e32 v54, 4, v51
	s_xor_b64 s[10:11], s[10:11], -1
	s_add_i32 s2, s2, 4
	s_add_i32 s7, s0, 0x10000
	v_bitop3_b32 v53, v98, v52, v53 bitop3:0xde
	v_lshlrev_b32_e32 v52, 3, v51
	v_and_b32_e32 v54, 0xc0, v54
	v_lshlrev_b32_e32 v55, 1, v51
	v_and_or_b32 v54, v52, 24, v54
	v_and_b32_e32 v55, 32, v55
	v_and_b32_e32 v52, 0x100, v52
	s_cmp_lg_u32 0, -1
	v_or3_b32 v52, v54, v55, v52
	s_cselect_b32 s0, 0, 0
	v_add_u32_e32 v185, s0, v52
	v_and_b32_e32 v52, 1, v165
	v_cmp_eq_u32_e32 vcc, 1, v52
	v_max_f32_e32 v52, v19, v19
	v_max_f32_e32 v54, v18, v18
	v_max_f32_e32 v52, v54, v52
	v_max3_f32 v52, v52, v20, v21
	v_max3_f32 v52, v52, v22, v23
	v_max3_f32 v52, v52, v24, v25
	v_max3_f32 v52, v52, v26, v27
	v_max3_f32 v52, v52, v28, v29
	v_max3_f32 v52, v52, v30, v31
	v_max3_f32 v52, v52, v32, v33
	v_max3_f32 v52, v52, v2, v3
	v_max3_f32 v52, v52, v4, v5
	v_max3_f32 v52, v52, v6, v7
	v_max3_f32 v52, v52, v8, v9
	v_max3_f32 v52, v52, v10, v11
	s_cmp_lt_i32 s44, 1
	v_max3_f32 v52, v52, v12, v13
	s_cselect_b64 s[0:1], -1, 0
	v_max3_f32 v52, v52, v14, v15
	v_max3_f32 v52, v52, v16, v17
	s_or_b64 vcc, s[0:1], vcc
	v_cndmask_b32_e32 v52, v220, v52, vcc
	v_mov_b32_e32 v54, v52
	s_nop 1
	v_permlane32_swap_b32_e32 v52, v54
	v_max_f32_e32 v54, v54, v54
	v_max_f32_e32 v52, v52, v52
	v_max_f32_e32 v52, v52, v54
	v_add_f32_e32 v54, 0x7149f2ca, v52
	v_mul_f32_e32 v54, 0x3db504f3, v54
	v_max_f32_e32 v52, 0xf149f2ca, v52
	v_cmp_ge_f32_e64 s[38:39], s91, v54
	v_sub_f32_e32 v54, 0xf149f2ca, v52
	v_mul_f32_e32 v54, 0x3e0293ee, v54
	s_cmp_eq_u64 s[38:39], exec
	v_exp_f32_e32 v54, v54
	s_cselect_b64 s[38:39], -1, 0
	v_mov_b32_e32 v55, 0xf149f2ca
	v_cndmask_b32_e64 v198, v52, v55, s[38:39]
	v_mul_f32_e32 v52, 0xbe0293ee, v198
	v_cndmask_b32_e32 v52, v220, v52, vcc
	v_cndmask_b32_e64 v196, v54, 1.0, s[38:39]
	v_mov_b32_e32 v54, v52
	v_fmamk_f32 v18, v18, 0x3e0293ee, v52
	v_fmamk_f32 v19, v19, 0x3e0293ee, v52
	v_fmamk_f32 v20, v20, 0x3e0293ee, v52
	v_fmamk_f32 v21, v21, 0x3e0293ee, v52
	v_fmamk_f32 v22, v22, 0x3e0293ee, v52
	v_fmamk_f32 v23, v23, 0x3e0293ee, v52
	v_fmamk_f32 v24, v24, 0x3e0293ee, v52
	v_fmamk_f32 v25, v25, 0x3e0293ee, v52
	v_fmamk_f32 v26, v26, 0x3e0293ee, v52
	v_fmamk_f32 v27, v27, 0x3e0293ee, v52
	v_fmamk_f32 v28, v28, 0x3e0293ee, v52
	v_fmamk_f32 v29, v29, 0x3e0293ee, v52
	v_fmamk_f32 v30, v30, 0x3e0293ee, v52
	v_fmamk_f32 v31, v31, 0x3e0293ee, v52
	v_fmamk_f32 v32, v32, 0x3e0293ee, v52
	v_fmac_f32_e32 v54, 0x3e0293ee, v33
	s_add_i32 s0, s6, 0xbfffff45
	v_pk_fma_f32 v[178:179], v[2:3], s[20:21], v[52:53] op_sel_hi:[1,0,0]
	v_exp_f32_e32 v231, v18
	v_exp_f32_e32 v233, v19
	v_exp_f32_e32 v229, v20
	v_exp_f32_e32 v232, v21
	v_exp_f32_e32 v228, v22
	v_exp_f32_e32 v230, v23
	v_exp_f32_e32 v226, v24
	v_exp_f32_e32 v227, v25
	v_exp_f32_e32 v223, v26
	v_exp_f32_e32 v225, v27
	v_exp_f32_e32 v209, v28
	v_exp_f32_e32 v224, v29
	v_exp_f32_e32 v206, v30
	v_exp_f32_e32 v208, v31
	v_exp_f32_e32 v205, v32
	v_exp_f32_e32 v207, v54
	v_add_u32_e32 v2, s0, v184
	s_waitcnt vmcnt(0)
	v_add_u32_e32 v188, 0, v53
	v_cmp_gt_u32_e64 s[38:39], 32, v51
	v_lshl_add_u32 v186, v50, 2, s7
	v_sub_u32_e32 v197, v2, v50
	v_mov_b32_e32 v50, v99
	v_mov_b32_e32 v51, v99
	v_pk_fma_f32 v[154:155], v[16:17], s[20:21], v[52:53] op_sel_hi:[1,0,0]
	v_pk_fma_f32 v[160:161], v[14:15], s[20:21], v[52:53] op_sel_hi:[1,0,0]
	v_pk_fma_f32 v[180:181], v[12:13], s[20:21], v[52:53] op_sel_hi:[1,0,0]
	v_pk_fma_f32 v[152:153], v[10:11], s[20:21], v[52:53] op_sel_hi:[1,0,0]
	v_pk_fma_f32 v[156:157], v[8:9], s[20:21], v[52:53] op_sel_hi:[1,0,0]
	v_pk_fma_f32 v[158:159], v[6:7], s[20:21], v[52:53] op_sel_hi:[1,0,0]
	v_pk_fma_f32 v[162:163], v[4:5], s[20:21], v[52:53] op_sel_hi:[1,0,0]
	s_waitcnt vmcnt(3)
	ds_write_b128 v191, v[34:37] offset:16384
	s_waitcnt vmcnt(2)
	ds_write_b128 v192, v[38:41] offset:16384
	s_waitcnt vmcnt(1)
	ds_write_b128 v188, v[42:45] offset:49152
	s_waitcnt vmcnt(0)
	ds_write_b128 v188, v[46:49] offset:57344
	v_mov_b32_e32 v52, v99
	v_mov_b32_e32 v53, v99
	v_mov_b32_e32 v54, v99
	v_mov_b32_e32 v55, v99
	v_mov_b32_e32 v56, v99
	v_mov_b32_e32 v57, v99
	v_mov_b32_e32 v58, v99
	v_mov_b32_e32 v59, v99
	v_mov_b32_e32 v60, v99
	v_mov_b32_e32 v61, v99
	v_mov_b32_e32 v62, v99
	v_mov_b32_e32 v63, v99
	v_mov_b32_e32 v64, v99
	v_mov_b32_e32 v65, v99
	v_mov_b64_e32 v[34:35], v[50:51]
	v_mov_b64_e32 v[18:19], v[50:51]
	v_mov_b64_e32 v[2:3], v[50:51]
	s_mov_b32 s3, 3
	v_lshl_add_u64 v[170:171], s[22:23], 0, v[98:99]
	v_lshl_add_u64 v[176:177], s[30:31], 0, v[98:99]
	v_lshl_add_u32 v187, v184, 2, s7
	v_mov_b32_e32 v189, 0
	s_movk_i32 s7, 0x7f
	v_mov_b64_e32 v[36:37], v[52:53]
	v_mov_b64_e32 v[38:39], v[54:55]
	v_mov_b64_e32 v[40:41], v[56:57]
	v_mov_b64_e32 v[42:43], v[58:59]
	v_mov_b64_e32 v[44:45], v[60:61]
	v_mov_b64_e32 v[46:47], v[62:63]
	v_mov_b64_e32 v[48:49], v[64:65]
	v_mov_b64_e32 v[20:21], v[52:53]
	v_mov_b64_e32 v[22:23], v[54:55]
	v_mov_b64_e32 v[24:25], v[56:57]
	v_mov_b64_e32 v[26:27], v[58:59]
	v_mov_b64_e32 v[28:29], v[60:61]
	v_mov_b64_e32 v[30:31], v[62:63]
	v_mov_b64_e32 v[32:33], v[64:65]
	v_mov_b64_e32 v[4:5], v[52:53]
	v_mov_b64_e32 v[6:7], v[54:55]
	v_mov_b64_e32 v[8:9], v[56:57]
	v_mov_b64_e32 v[10:11], v[58:59]
	v_mov_b64_e32 v[12:13], v[60:61]
	v_mov_b64_e32 v[14:15], v[62:63]
	v_mov_b64_e32 v[16:17], v[64:65]
	s_mov_b32 s100, 0
	s_waitcnt lgkmcnt(0)
	s_barrier
.LBB0_89:
	s_waitcnt vmcnt(0)
	s_cmp_eq_u32 s100, 0
	s_cbranch_scc1 .Lmy_hs1_nov
	ds_write_b128 v191, v[242:245] offset:16384
	ds_write_b128 v192, v[246:249] offset:16384
; __device__ __forceinline__ void finishSM(f32x16& p0, f32x16& p1, float alpha, float& l_reg, bf16x8& pa0, bf16x8& pa1, bf16x8& pa2, bf16x8& pa3) {
;     for (int r = 0; r < 16; ++r) p1[r] = __builtin_amdgcn_exp2f(p1[r]);
;     float ps = 0; for (int r = 0; r < 16; ++r) ps += p0[r]; for (int r = 0; r < 16; ++r) ps += p1[r];
;     { auto rr = __builtin_amdgcn_permlane32_swap(__float_as_uint(ps), __float_as_uint(ps), false, false);
;       ps = __uint_as_float(rr[0]) + __uint_as_float(rr[1]); }
;     l_reg = l_reg * alpha + ps;
;     ...
;     PK4(p0, 0, pa0); PK4(p0, 8, pa1); PK4(p1, 0, pa2); PK4(p1, 8, pa3);
;     ...
; }
; template <int KB>
; __device__ __forceinline__ void qkt(f32x16& p0, f32x16& p1, const char* K_lds, int r32, int hi, const bf16x8* qr) {
;     p0 = f32x16{}; p1 = f32x16{};
;     const char* kb[4];
; #pragma unroll
;     for (int dd = 0; dd < 4; ++dd) kb[dd] = K_lds + KB * SHM_K + KSWZ(r32, (dd * 16 + hi * 8) * 2);
; #pragma unroll
;     for (int d0 = 0; d0 < 8; ++d0) { const char* a = kb[d0 & 3] + (d0 >> 2) * 128;
;         bf16x8 b0 = *reinterpret_cast<const bf16x8*>(a);
;         bf16x8 b1 = *reinterpret_cast<const bf16x8*>(a + 32 * 256);
;         p0 = __builtin_amdgcn_mfma_f32_32x32x16_bf16(b0, qr[d0], p0, 0, 0, 0);
;         p1 = __builtin_amdgcn_mfma_f32_32x32x16_bf16(b1, qr[d0], p1, 0, 0, 0); }
.Lmy_hs1_nov:
	s_mov_b32 s100, 0
	ds_read_b128 v[66:69], v169 offset:49152
	ds_read_b128 v[70:73], v169 offset:57344
	ds_read_b128 v[100:103], v193 offset:49152
	ds_read_b128 v[136:139], v193 offset:57344
	s_waitcnt lgkmcnt(3)
	v_mfma_f32_32x32x16_bf16 v[82:97], v[66:69], v[132:135], 0
	v_add_f32_e32 v148, 0, v231
	v_add_f32_e32 v148, v233, v148
	v_add_f32_e32 v148, v229, v148
	v_add_f32_e32 v148, v232, v148
	v_add_f32_e32 v148, v228, v148
	s_waitcnt lgkmcnt(2)
	v_mfma_f32_32x32x16_bf16 v[66:81], v[70:73], v[132:135], 0
	v_add_f32_e32 v148, v230, v148
	v_add_f32_e32 v148, v226, v148
	v_add_f32_e32 v148, v227, v148
	v_add_f32_e32 v148, v223, v148
	v_add_f32_e32 v148, v225, v148
	s_waitcnt lgkmcnt(1)
	v_mfma_f32_32x32x16_bf16 v[82:97], v[100:103], v[128:131], v[82:97]
	v_add_f32_e32 v148, v209, v148
	v_add_f32_e32 v148, v224, v148
	v_add_f32_e32 v148, v206, v148
	v_add_f32_e32 v148, v208, v148
	v_add_f32_e32 v148, v205, v148
	s_waitcnt lgkmcnt(0)
	v_mfma_f32_32x32x16_bf16 v[66:81], v[136:139], v[128:131], v[66:81]
	v_add_f32_e32 v148, v207, v148
	v_exp_f32_e32 v140, v152
	v_exp_f32_e32 v141, v153
	v_exp_f32_e32 v142, v180
	v_exp_f32_e32 v143, v181
	ds_read_b128 v[100:103], v194 offset:49152
	ds_read_b128 v[136:139], v194 offset:57344
	s_waitcnt lgkmcnt(1)
	v_mfma_f32_32x32x16_bf16 v[82:97], v[100:103], v[124:127], v[82:97]
	v_exp_f32_e32 v144, v160
	v_exp_f32_e32 v145, v161
	v_exp_f32_e32 v146, v154
	v_exp_f32_e32 v147, v155
	v_exp_f32_e32 v178, v178
	s_waitcnt lgkmcnt(0)
	v_mfma_f32_32x32x16_bf16 v[66:81], v[136:139], v[124:127], v[66:81]
	v_exp_f32_e32 v179, v179
	v_exp_f32_e32 v162, v162
	v_exp_f32_e32 v163, v163
	v_add_f32_e32 v148, v178, v148
	v_add_f32_e32 v148, v179, v148
	ds_read_b128 v[100:103], v195 offset:49152
	ds_read_b128 v[136:139], v195 offset:57344
	s_waitcnt lgkmcnt(1)
	v_mfma_f32_32x32x16_bf16 v[82:97], v[100:103], v[120:123], v[82:97]
	v_add_f32_e32 v148, v162, v148
	v_exp_f32_e32 v158, v158
	v_exp_f32_e32 v159, v159
	v_exp_f32_e32 v156, v156
	v_exp_f32_e32 v157, v157
	s_waitcnt lgkmcnt(0)
	v_mfma_f32_32x32x16_bf16 v[66:81], v[136:139], v[120:123], v[66:81]
	v_add_f32_e32 v148, v163, v148
	v_add_f32_e32 v148, v158, v148
	v_add_f32_e32 v148, v159, v148
	v_add_f32_e32 v148, v156, v148
	v_add_f32_e32 v148, v157, v148
	ds_read_b128 v[100:103], v169 offset:49280
	ds_read_b128 v[136:139], v169 offset:57472
	s_waitcnt lgkmcnt(1)
	v_mfma_f32_32x32x16_bf16 v[82:97], v[100:103], v[116:119], v[82:97]
	v_add_f32_e32 v148, v140, v148
	v_add_f32_e32 v148, v141, v148
	v_add_f32_e32 v148, v142, v148
	v_add_f32_e32 v148, v143, v148
	v_add_f32_e32 v148, v144, v148
	s_waitcnt lgkmcnt(0)
	v_mfma_f32_32x32x16_bf16 v[66:81], v[136:139], v[116:119], v[66:81]
	v_add_f32_e32 v148, v145, v148
	v_add_f32_e32 v148, v146, v148
	v_add_f32_e32 v199, v147, v148
	v_mov_b32_e32 v200, v199
	s_nop 1
	v_permlane32_swap_b32_e32 v199, v200
	v_cvt_pk_bf16_f32 v148, v231, v233
	ds_read_b128 v[100:103], v193 offset:49280
	ds_read_b128 v[136:139], v193 offset:57472
	s_waitcnt lgkmcnt(1)
	v_mfma_f32_32x32x16_bf16 v[82:97], v[100:103], v[112:115], v[82:97]
	v_cvt_pk_bf16_f32 v149, v229, v232
	v_cvt_pk_bf16_f32 v150, v228, v230
	v_cvt_pk_bf16_f32 v151, v226, v227
	v_cvt_pk_bf16_f32 v152, v223, v225
	v_cvt_pk_bf16_f32 v153, v209, v224
	s_waitcnt lgkmcnt(0)
	v_mfma_f32_32x32x16_bf16 v[66:81], v[136:139], v[112:115], v[66:81]
	v_cvt_pk_bf16_f32 v154, v206, v208
	v_cvt_pk_bf16_f32 v155, v205, v207
	v_cvt_pk_bf16_f32 v158, v158, v159
	v_cvt_pk_bf16_f32 v159, v156, v157
	v_cvt_pk_bf16_f32 v156, v178, v179
	ds_read_b128 v[100:103], v194 offset:49280
	ds_read_b128 v[136:139], v194 offset:57472
	s_waitcnt lgkmcnt(1)
	v_mfma_f32_32x32x16_bf16 v[82:97], v[100:103], v[108:111], v[82:97]
	v_cvt_pk_bf16_f32 v157, v162, v163
	v_cvt_pk_bf16_f32 v160, v140, v141
	v_cvt_pk_bf16_f32 v161, v142, v143
	v_cvt_pk_bf16_f32 v162, v144, v145
	v_cvt_pk_bf16_f32 v163, v146, v147
	s_waitcnt lgkmcnt(0)
	v_mfma_f32_32x32x16_bf16 v[66:81], v[136:139], v[108:111], v[66:81]
	s_nop 0
	v_permlane32_swap_b32_e32 v148, v150
	v_permlane32_swap_b32_e32 v149, v151
	v_permlane32_swap_b32_e32 v152, v154
	v_permlane32_swap_b32_e32 v153, v155
	ds_read_b128 v[100:103], v195 offset:49280
	ds_read_b128 v[136:139], v195 offset:57472
	s_waitcnt lgkmcnt(1)
	v_mfma_f32_32x32x16_bf16 v[82:97], v[100:103], v[104:107], v[82:97]
	v_permlane32_swap_b32_e32 v156, v158
	v_permlane32_swap_b32_e32 v157, v159
	v_permlane32_swap_b32_e32 v160, v162
	v_permlane32_swap_b32_e32 v161, v163
	s_waitcnt lgkmcnt(0)
	v_mfma_f32_32x32x16_bf16 v[66:81], v[136:139], v[104:107], v[66:81]
	v_add_u32_e32 v178, s7, v166
	v_add_u32_e32 v100, 1, v178
	v_add_u32_e32 v102, 33, v178
	v_ashrrev_i32_e32 v101, 31, v100
	v_ashrrev_i32_e32 v103, 31, v102
	v_lshlrev_b64 v[140:141], 8, v[100:101]
	v_lshlrev_b64 v[142:143], 8, v[102:103]
	v_lshl_add_u64 v[100:101], v[170:171], 0, v[140:141]
	v_lshl_add_u64 v[136:137], v[170:171], 0, v[142:143]
	v_lshl_add_u64 v[140:141], v[176:177], 0, v[140:141]
	v_lshl_add_u64 v[144:145], v[176:177], 0, v[142:143]
	global_load_dwordx4 v[100:103], v[100:101], off
	s_nop 0
	global_load_dwordx4 v[136:139], v[136:137], off
	s_nop 0
	global_load_dwordx4 v[140:143], v[140:141], off
	s_nop 0
	global_load_dwordx4 v[144:147], v[144:145], off
	ds_read_b64_tr_b16 v[172:173], v185 offset:0
	ds_read_b64_tr_b16 v[174:175], v185 offset:0x800
	ds_read_b64_tr_b16 v[202:203], v185 offset:0x1000
	ds_read_b64_tr_b16 v[204:205], v185 offset:0x1800
	ds_read_b64_tr_b16 v[206:207], v185 offset:0x2000
	ds_read_b64_tr_b16 v[208:209], v185 offset:0x2800
	ds_read_b64_tr_b16 v[224:225], v185 offset:0x3000
	ds_read_b64_tr_b16 v[226:227], v185 offset:0x3800
	s_waitcnt lgkmcnt(0)
; __device__ __forceinline__ void mask_tile(f32x16& p0, f32x16& p1, int dq, unsigned W) {
;     const float NEG = -__builtin_inff();
; #pragma unroll
;     for (int r = 0; r < 16; ++r) {
;         const int c = (r & 3) + 8 * (r >> 2);
;         if ((unsigned)(dq - c) >= W) p0[r] = NEG;
;         if ((unsigned)(dq - c - 32) >= W) p1[r] = NEG;
;     }
; }
; template <int VB>
; __device__ __forceinline__ void pv_tile(f32x16* o, int vb0, bf16x8 pa0, bf16x8 pa1, bf16x8 pa2, bf16x8 pa3) {
;     ...
;     PV_D0(0); PV_D0(1); PV_D0(2); PV_D0(3);
	s_nop 0
	v_mfma_f32_32x32x16_bf16 v[50:65], v[148:151], v[172:175], v[50:65]
	ds_read_b64_tr_b16 v[172:173], v185 offset:0x200
	ds_read_b64_tr_b16 v[174:175], v185 offset:0xa00
	v_mfma_f32_32x32x16_bf16 v[50:65], v[152:155], v[202:205], v[50:65]
	ds_read_b64_tr_b16 v[202:203], v185 offset:0x1200
	ds_read_b64_tr_b16 v[204:205], v185 offset:0x1a00
	v_mfma_f32_32x32x16_bf16 v[50:65], v[156:159], v[206:209], v[50:65]
	ds_read_b64_tr_b16 v[206:207], v185 offset:0x2200
	ds_read_b64_tr_b16 v[208:209], v185 offset:0x2a00
	v_mfma_f32_32x32x16_bf16 v[50:65], v[160:163], v[224:227], v[50:65]
	ds_read_b64_tr_b16 v[224:225], v185 offset:0x3200
	ds_read_b64_tr_b16 v[226:227], v185 offset:0x3a00
	s_waitcnt lgkmcnt(0)
	v_mfma_f32_32x32x16_bf16 v[34:49], v[148:151], v[172:175], v[34:49]
	ds_read_b64_tr_b16 v[172:173], v185 offset:0x400
	ds_read_b64_tr_b16 v[174:175], v185 offset:0xc00
	v_mfma_f32_32x32x16_bf16 v[34:49], v[152:155], v[202:205], v[34:49]
	ds_read_b64_tr_b16 v[202:203], v185 offset:0x1400
	ds_read_b64_tr_b16 v[204:205], v185 offset:0x1c00
	v_mfma_f32_32x32x16_bf16 v[34:49], v[156:159], v[206:209], v[34:49]
	ds_read_b64_tr_b16 v[206:207], v185 offset:0x2400
	ds_read_b64_tr_b16 v[208:209], v185 offset:0x2c00
	v_mfma_f32_32x32x16_bf16 v[34:49], v[160:163], v[224:227], v[34:49]
	ds_read_b64_tr_b16 v[224:225], v185 offset:0x3400
	ds_read_b64_tr_b16 v[226:227], v185 offset:0x3c00
	s_waitcnt lgkmcnt(0)
	v_mfma_f32_32x32x16_bf16 v[18:33], v[148:151], v[172:175], v[18:33]
	ds_read_b64_tr_b16 v[172:173], v185 offset:0x600
	ds_read_b64_tr_b16 v[174:175], v185 offset:0xe00
	v_mfma_f32_32x32x16_bf16 v[18:33], v[152:155], v[202:205], v[18:33]
	ds_read_b64_tr_b16 v[202:203], v185 offset:0x1600
	ds_read_b64_tr_b16 v[204:205], v185 offset:0x1e00
	v_mfma_f32_32x32x16_bf16 v[18:33], v[156:159], v[206:209], v[18:33]
	ds_read_b64_tr_b16 v[206:207], v185 offset:0x2600
	ds_read_b64_tr_b16 v[208:209], v185 offset:0x2e00
	v_mfma_f32_32x32x16_bf16 v[18:33], v[160:163], v[224:227], v[18:33]
	ds_read_b64_tr_b16 v[224:225], v185 offset:0x3600
	ds_read_b64_tr_b16 v[226:227], v185 offset:0x3e00
	s_waitcnt lgkmcnt(0)
	v_mfma_f32_32x32x16_bf16 v[2:17], v[148:151], v[172:175], v[2:17]
	s_cmp_le_i32 s7, s6
	v_mfma_f32_32x32x16_bf16 v[2:17], v[152:155], v[202:205], v[2:17]
	v_mfma_f32_32x32x16_bf16 v[2:17], v[156:159], v[206:209], v[2:17]
	v_mfma_f32_32x32x16_bf16 v[2:17], v[160:163], v[224:227], v[2:17]
	s_cbranch_scc1 .LBB0_91
	v_add_u32_e32 v148, 0x4000007b, v197
	v_cmp_gt_u32_e32 vcc, 2.0, v148
	v_add_u32_e32 v148, 0x5b, v197
	s_nop 0
	v_cndmask_b32_e32 v82, v220, v82, vcc
	v_cmp_lt_u32_e32 vcc, s33, v148
	v_add_u32_e32 v148, 0x7a, v197
	s_nop 0
	v_cndmask_b32_e32 v66, v220, v66, vcc
	v_cmp_lt_u32_e32 vcc, s33, v148
	v_add_u32_e32 v148, 0x5a, v197
	s_nop 0
	v_cndmask_b32_e32 v83, v220, v83, vcc
	v_cmp_lt_u32_e32 vcc, s33, v148
	v_add_u32_e32 v148, 0x79, v197
	s_nop 0
	v_cndmask_b32_e32 v67, v220, v67, vcc
	v_cmp_lt_u32_e32 vcc, s33, v148
	v_add_u32_e32 v148, 0x59, v197
	s_nop 0
	v_cndmask_b32_e32 v84, v220, v84, vcc
	v_cmp_lt_u32_e32 vcc, s33, v148
	v_add_u32_e32 v148, 0x78, v197
	s_nop 0
	v_cndmask_b32_e32 v68, v220, v68, vcc
	v_cmp_lt_u32_e32 vcc, s33, v148
	v_add_u32_e32 v148, 0x58, v197
	s_nop 0
	v_cndmask_b32_e32 v85, v220, v85, vcc
	v_cmp_lt_u32_e32 vcc, s33, v148
	v_add_u32_e32 v148, 0x73, v197
	s_nop 0
	v_cndmask_b32_e32 v69, v220, v69, vcc
	v_cmp_lt_u32_e32 vcc, s33, v148
	v_add_u32_e32 v148, 0x53, v197
	s_nop 0
	v_cndmask_b32_e32 v86, v220, v86, vcc
	v_cmp_lt_u32_e32 vcc, s33, v148
	v_add_u32_e32 v148, 0x72, v197
	s_nop 0
	v_cndmask_b32_e32 v70, v220, v70, vcc
	v_cmp_lt_u32_e32 vcc, s33, v148
	v_add_u32_e32 v148, 0x52, v197
	s_nop 0
	v_cndmask_b32_e32 v87, v220, v87, vcc
	v_cmp_lt_u32_e32 vcc, s33, v148
	v_add_u32_e32 v148, 0x71, v197
	s_nop 0
	v_cndmask_b32_e32 v71, v220, v71, vcc
	v_cmp_lt_u32_e32 vcc, s33, v148
	v_add_u32_e32 v148, 0x51, v197
	s_nop 0
	v_cndmask_b32_e32 v88, v220, v88, vcc
	v_cmp_lt_u32_e32 vcc, s33, v148
	v_add_u32_e32 v148, 0x70, v197
	s_nop 0
	v_cndmask_b32_e32 v72, v220, v72, vcc
	v_cmp_lt_u32_e32 vcc, s33, v148
	v_add_u32_e32 v148, 0x50, v197
	s_nop 0
	v_cndmask_b32_e32 v89, v220, v89, vcc
	v_cmp_lt_u32_e32 vcc, s33, v148
	v_add_u32_e32 v148, 0x6b, v197
	s_nop 0
	v_cndmask_b32_e32 v73, v220, v73, vcc
	v_cmp_lt_u32_e32 vcc, s33, v148
	v_add_u32_e32 v148, 0x4b, v197
	s_nop 0
	v_cndmask_b32_e32 v90, v220, v90, vcc
	v_cmp_lt_u32_e32 vcc, s33, v148
	v_add_u32_e32 v148, 0x6a, v197
	s_nop 0
	v_cndmask_b32_e32 v74, v220, v74, vcc
	v_cmp_lt_u32_e32 vcc, s33, v148
	v_add_u32_e32 v148, 0x4a, v197
	s_nop 0
	v_cndmask_b32_e32 v91, v220, v91, vcc
	v_cmp_lt_u32_e32 vcc, s33, v148
	v_add_u32_e32 v148, 0x69, v197
	s_nop 0
	v_cndmask_b32_e32 v75, v220, v75, vcc
	v_cmp_lt_u32_e32 vcc, s33, v148
	v_add_u32_e32 v148, 0x49, v197
	s_nop 0
	v_cndmask_b32_e32 v92, v220, v92, vcc
	v_cmp_lt_u32_e32 vcc, s33, v148
	v_add_u32_e32 v148, 0x68, v197
	s_nop 0
	v_cndmask_b32_e32 v76, v220, v76, vcc
	v_cmp_lt_u32_e32 vcc, s33, v148
	v_add_u32_e32 v148, 0x48, v197
	s_nop 0
	v_cndmask_b32_e32 v93, v220, v93, vcc
	v_cmp_lt_u32_e32 vcc, s33, v148
	v_add_u32_e32 v148, 0x63, v197
	s_nop 0
	v_cndmask_b32_e32 v77, v220, v77, vcc
	v_cmp_lt_u32_e32 vcc, s33, v148
	v_add_u32_e32 v148, 0x43, v197
	s_nop 0
	v_cndmask_b32_e32 v94, v220, v94, vcc
	v_cmp_lt_u32_e32 vcc, s33, v148
	v_add_u32_e32 v148, 0x62, v197
	s_nop 0
	v_cndmask_b32_e32 v78, v220, v78, vcc
	v_cmp_lt_u32_e32 vcc, s33, v148
	v_add_u32_e32 v148, 0x42, v197
	s_nop 0
	v_cndmask_b32_e32 v95, v220, v95, vcc
	v_cmp_lt_u32_e32 vcc, s33, v148
	v_add_u32_e32 v148, 0x61, v197
	s_nop 0
	v_cndmask_b32_e32 v79, v220, v79, vcc
	v_cmp_lt_u32_e32 vcc, s33, v148
	v_add_u32_e32 v148, 0x41, v197
	s_nop 0
	v_cndmask_b32_e32 v96, v220, v96, vcc
	v_cmp_lt_u32_e32 vcc, s33, v148
	v_add_u32_e32 v148, 0x60, v197
	s_nop 0
	v_cndmask_b32_e32 v80, v220, v80, vcc
	v_cmp_lt_u32_e32 vcc, s33, v148
	v_add_u32_e32 v148, 64, v197
	s_nop 0
	v_cndmask_b32_e32 v97, v220, v97, vcc
	v_cmp_lt_u32_e32 vcc, s33, v148
	s_nop 1
	v_cndmask_b32_e32 v81, v220, v81, vcc
; #define SBAR() __builtin_amdgcn_sched_barrier(0)
; #define VMW() asm volatile("s_waitcnt vmcnt(0)" ::: "memory")
; #define SLOAD_H(Kp, Vp, k0) do { S.st_v0 = load8(ROW(Vp, k0, sr)); S.st_v1 = load8(ROW(Vp, k0, 32 + sr));              \
;                          S.st_k0 = load8(ROW(Kp, k0, sr)); S.st_k1 = load8(ROW(Kp, k0, 32 + sr)); } while (0)
; #define SWRITE_HV(bf) do { *(bf16x8*)(V_lds + (bf) * SHM_V + vst0) = S.st_v0; *(bf16x8*)(V_lds + (bf) * SHM_V + vst1) = S.st_v1; } while (0)
; #define SWRITE_H(bf) do { SWRITE_HV(bf); SWRITE_HK(bf); } while (0)
; #define MASKT(P0_, P1_, t) do { const int kb_ = KBASE(t); if (kb_ + KVBLK - 1 > qlo) mask_tile(P0_, P1_, qm - kb_, (unsigned)W); } while (0)
; __device__ __forceinline__ void partialSM(f32x16& p0, f32x16& p1, float& m_reg, float& mn, float& alpha, bool rs) {
;     float pmax = p0[0]; for (int r = 1; r < 16; ++r) pmax = fmaxf(pmax, p0[r]); for (int r = 0; r < 16; ++r) pmax = fmaxf(pmax, p1[r]);
;     if (!rs) pmax = -__builtin_inff();
;     { auto rr = __builtin_amdgcn_permlane32_swap(__float_as_uint(pmax), __float_as_uint(pmax), false, false);
;       pmax = fmaxf(__uint_as_float(rr[0]), __uint_as_float(rr[1])); }
;     constexpr float C2 = 1.4426950408889634f * SCALE;
;     if (__builtin_expect(__all((pmax - m_reg) * SCALE <= THR), 1)) { mn = m_reg; alpha = 1.f; }
;     else { mn = fmaxf(m_reg, pmax); alpha = __builtin_amdgcn_exp2f((m_reg - mn) * C2); m_reg = mn; }
;     const float mnL = rs ? -mn * C2 : -__builtin_inff();
;     for (int r = 0; r < 16; ++r) p0[r] = fmaf(p0[r], C2, mnL); for (int r = 0; r < 16; ++r) p1[r] = fmaf(p1[r], C2, mnL);
;     for (int r = 0; r < 16; ++r) p0[r] = __builtin_amdgcn_exp2f(p0[r]);
; }
; __device__ __forceinline__ void moba_block(const BlockRef& cur, const BlockRef& nxt, char* lds, Seam& S) {
;     ...
;     constexpr int NQL = 8;
;     ...
;     f32x16 pA0, pA1, pB0, pB1; float mnA, mnB, alA, alB; bf16x8 pa0, pa1, pa2, pa3;
;     SWRITE_HV(0); SBAR();
;     if (NT > 1) { SLOAD_H(Kh, Vh, KBASE(1)); }
;     SBAR(); qkt<0>(pA0, pA1, K_lds, r32, hi, S.qr);
;     MASKT(pA0, pA1, 0); partialSM(pA0, pA1, m_reg, mnA, alA, RSEL(0));
;     if (NT > 1) { VMW(); SWRITE_H(1); }
;     __syncthreads();
.LBB0_91:
	s_add_i32 s0, s3, -2
	s_lshr_b32 s8, s0, 2
	s_cmp_ge_i32 s8, s44
	s_cselect_b64 s[0:1], -1, 0
	s_lshl_b32 s8, 1, s8
	v_and_b32_e32 v148, s8, v165
	v_cmp_ne_u32_e32 vcc, 0, v148
	v_max_f32_e32 v148, v83, v83
	v_max_f32_e32 v149, v82, v82
	v_max_f32_e32 v148, v149, v148
	v_max3_f32 v148, v148, v84, v85
	v_max3_f32 v148, v148, v86, v87
	v_max3_f32 v148, v148, v88, v89
	v_max3_f32 v148, v148, v90, v91
	v_max3_f32 v148, v148, v92, v93
	v_max3_f32 v148, v148, v94, v95
	v_max3_f32 v148, v148, v96, v97
	v_max3_f32 v148, v148, v66, v67
	v_max3_f32 v148, v148, v68, v69
	v_max3_f32 v148, v148, v70, v71
	v_max3_f32 v148, v148, v72, v73
	v_max3_f32 v148, v148, v74, v75
	v_max3_f32 v148, v148, v76, v77
	v_max3_f32 v148, v148, v78, v79
	s_or_b64 s[40:41], s[0:1], vcc
	v_max3_f32 v148, v148, v80, v81
	v_cndmask_b32_e64 v148, v220, v148, s[40:41]
	v_mov_b32_e32 v149, v148
	s_nop 1
	v_permlane32_swap_b32_e32 v148, v149
	v_max_f32_e32 v149, v149, v149
	v_max_f32_e32 v148, v148, v148
	v_max_f32_e32 v148, v148, v149
	v_sub_f32_e32 v149, v148, v198
	v_mul_f32_e32 v149, 0x3db504f3, v149
	v_cmp_ge_f32_e32 vcc, s91, v149
	v_max_f32_e32 v149, v198, v198
	v_max_f32_e32 v148, v149, v148
	v_sub_f32_e32 v149, v198, v148
	v_mul_f32_e32 v149, 0x3e0293ee, v149
	v_exp_f32_e32 v149, v149
	s_cmp_eq_u64 vcc, exec
	s_cselect_b64 s[42:43], -1, 0
	s_waitcnt vmcnt(0)
	v_cndmask_b32_e64 v202, v149, 1.0, s[42:43]
	v_cmp_gt_f32_e32 vcc, 1.0, v202
	s_waitcnt vmcnt(1)
	ds_write_b128 v188, v[140:143] offset:32768
	s_waitcnt vmcnt(0)
	ds_write_b128 v188, v[144:147] offset:40960
	s_cbranch_vccz .LBB0_95
	s_and_saveexec_b64 s[0:1], s[38:39]
	ds_write_b32 v187, v202 offset:128
	s_or_b64 exec, exec, s[0:1]
	s_waitcnt lgkmcnt(0)
	ds_read_b128 v[150:153], v186 offset:224
	ds_read_b128 v[154:157], v186 offset:192
	ds_read_b128 v[158:161], v186 offset:160
	ds_read_b128 v[172:175], v186 offset:128
	s_waitcnt lgkmcnt(3)
	v_pk_mul_f32 v[64:65], v[64:65], v[152:153]
	s_waitcnt lgkmcnt(2)
	v_pk_mul_f32 v[60:61], v[60:61], v[156:157]
	s_waitcnt lgkmcnt(1)
	v_pk_mul_f32 v[56:57], v[56:57], v[160:161]
	s_waitcnt lgkmcnt(0)
	v_pk_mul_f32 v[52:53], v[52:53], v[174:175]
	v_pk_mul_f32 v[62:63], v[62:63], v[150:151]
	v_pk_mul_f32 v[58:59], v[58:59], v[154:155]
	v_pk_mul_f32 v[54:55], v[54:55], v[158:159]
	v_pk_mul_f32 v[50:51], v[50:51], v[172:173]
	v_pk_mul_f32 v[48:49], v[48:49], v[152:153]
	v_pk_mul_f32 v[44:45], v[44:45], v[156:157]
	v_pk_mul_f32 v[40:41], v[40:41], v[160:161]
	v_pk_mul_f32 v[36:37], v[36:37], v[174:175]
	v_pk_mul_f32 v[46:47], v[46:47], v[150:151]
	v_pk_mul_f32 v[42:43], v[42:43], v[154:155]
	v_pk_mul_f32 v[38:39], v[38:39], v[158:159]
	v_pk_mul_f32 v[34:35], v[34:35], v[172:173]
	v_pk_mul_f32 v[32:33], v[32:33], v[152:153]
	v_pk_mul_f32 v[28:29], v[28:29], v[156:157]
	v_pk_mul_f32 v[24:25], v[24:25], v[160:161]
	v_pk_mul_f32 v[20:21], v[20:21], v[174:175]
	v_pk_mul_f32 v[30:31], v[30:31], v[150:151]
	v_pk_mul_f32 v[26:27], v[26:27], v[154:155]
	v_pk_mul_f32 v[22:23], v[22:23], v[158:159]
	v_pk_mul_f32 v[18:19], v[18:19], v[172:173]
	v_pk_mul_f32 v[16:17], v[16:17], v[152:153]
	v_pk_mul_f32 v[12:13], v[12:13], v[156:157]
	v_pk_mul_f32 v[8:9], v[8:9], v[160:161]
	v_pk_mul_f32 v[4:5], v[4:5], v[174:175]
	v_pk_mul_f32 v[14:15], v[14:15], v[150:151]
	v_pk_mul_f32 v[10:11], v[10:11], v[154:155]
	v_pk_mul_f32 v[6:7], v[6:7], v[158:159]
	v_pk_mul_f32 v[2:3], v[2:3], v[172:173]
.LBB0_95:
	v_cndmask_b32_e64 v179, v148, v198, s[42:43]
	v_mul_f32_e32 v148, 0xbe0293ee, v179
	v_cndmask_b32_e64 v180, v220, v148, s[40:41]
	v_fmamk_f32 v82, v82, 0x3e0293ee, v180
	v_fmamk_f32 v83, v83, 0x3e0293ee, v180
	v_fmamk_f32 v84, v84, 0x3e0293ee, v180
	v_fmamk_f32 v85, v85, 0x3e0293ee, v180
	v_fmamk_f32 v86, v86, 0x3e0293ee, v180
	v_fmamk_f32 v87, v87, 0x3e0293ee, v180
	v_fmamk_f32 v88, v88, 0x3e0293ee, v180
	v_fmamk_f32 v89, v89, 0x3e0293ee, v180
	v_fmamk_f32 v90, v90, 0x3e0293ee, v180
	v_fmamk_f32 v91, v91, 0x3e0293ee, v180
	v_fmamk_f32 v92, v92, 0x3e0293ee, v180
	v_fmamk_f32 v93, v93, 0x3e0293ee, v180
	v_fmamk_f32 v94, v94, 0x3e0293ee, v180
	v_fmamk_f32 v95, v95, 0x3e0293ee, v180
	v_fmamk_f32 v96, v96, 0x3e0293ee, v180
	v_fmamk_f32 v97, v97, 0x3e0293ee, v180
	v_exp_f32_e32 v148, v82
	v_exp_f32_e32 v163, v83
	v_exp_f32_e32 v149, v84
	v_exp_f32_e32 v162, v85
	v_exp_f32_e32 v150, v86
	v_exp_f32_e32 v161, v87
	v_exp_f32_e32 v151, v88
	v_exp_f32_e32 v160, v89
	v_exp_f32_e32 v152, v90
	v_exp_f32_e32 v159, v91
	v_exp_f32_e32 v153, v92
	v_exp_f32_e32 v158, v93
	v_exp_f32_e32 v154, v94
	v_exp_f32_e32 v157, v95
	v_exp_f32_e32 v155, v96
	v_exp_f32_e32 v156, v97
	v_fmamk_f32 v203, v73, 0x3e0293ee, v180
	v_fmamk_f32 v204, v74, 0x3e0293ee, v180
	v_fmamk_f32 v208, v66, 0x3e0293ee, v180
	v_fmamk_f32 v209, v67, 0x3e0293ee, v180
	v_fmamk_f32 v223, v68, 0x3e0293ee, v180
	v_fmamk_f32 v224, v69, 0x3e0293ee, v180
	v_fmamk_f32 v225, v70, 0x3e0293ee, v180
	v_fmamk_f32 v198, v71, 0x3e0293ee, v180
	v_fmamk_f32 v201, v72, 0x3e0293ee, v180
	v_fmamk_f32 v205, v75, 0x3e0293ee, v180
	v_fmamk_f32 v206, v76, 0x3e0293ee, v180
	v_fmamk_f32 v207, v77, 0x3e0293ee, v180
	v_fmamk_f32 v181, v78, 0x3e0293ee, v180
	v_fmamk_f32 v226, v79, 0x3e0293ee, v180
	v_fmamk_f32 v227, v80, 0x3e0293ee, v180
	v_fmac_f32_e32 v180, 0x3e0293ee, v81
	s_waitcnt lgkmcnt(0)
	s_barrier
; __device__ __forceinline__ void finishSM(f32x16& p0, f32x16& p1, float alpha, float& l_reg, bf16x8& pa0, bf16x8& pa1, bf16x8& pa2, bf16x8& pa3) {
;     for (int r = 0; r < 16; ++r) p1[r] = __builtin_amdgcn_exp2f(p1[r]);
;     float ps = 0; for (int r = 0; r < 16; ++r) ps += p0[r]; for (int r = 0; r < 16; ++r) ps += p1[r];
;     { auto rr = __builtin_amdgcn_permlane32_swap(__float_as_uint(ps), __float_as_uint(ps), false, false);
;       ps = __uint_as_float(rr[0]) + __uint_as_float(rr[1]); }
;     l_reg = l_reg * alpha + ps;
;     ...
;     PK4(p0, 0, pa0); PK4(p0, 8, pa1); PK4(p1, 0, pa2); PK4(p1, 8, pa3);
;     ...
; }
; template <int KB>
; __device__ __forceinline__ void qkt(f32x16& p0, f32x16& p1, const char* K_lds, int r32, int hi, const bf16x8* qr) {
;     p0 = f32x16{}; p1 = f32x16{};
;     const char* kb[4];
; #pragma unroll
;     for (int dd = 0; dd < 4; ++dd) kb[dd] = K_lds + KB * SHM_K + KSWZ(r32, (dd * 16 + hi * 8) * 2);
; #pragma unroll
;     for (int d0 = 0; d0 < 8; ++d0) { const char* a = kb[d0 & 3] + (d0 >> 2) * 128;
;         bf16x8 b0 = *reinterpret_cast<const bf16x8*>(a);
;         bf16x8 b1 = *reinterpret_cast<const bf16x8*>(a + 32 * 256);
;         p0 = __builtin_amdgcn_mfma_f32_32x32x16_bf16(b0, qr[d0], p0, 0, 0, 0);
;         p1 = __builtin_amdgcn_mfma_f32_32x32x16_bf16(b1, qr[d0], p1, 0, 0, 0); }
	s_waitcnt vmcnt(0)
	ds_write_b128 v191, v[100:103]
	ds_write_b128 v192, v[136:139]
	ds_read_b128 v[66:69], v169 offset:32768
	ds_read_b128 v[70:73], v169 offset:40960
	ds_read_b128 v[172:175], v193 offset:32768
	ds_read_b128 v[228:231], v193 offset:40960
	s_waitcnt lgkmcnt(3)
	v_mfma_f32_32x32x16_bf16 v[82:97], v[66:69], v[132:135], 0
	v_exp_f32_e32 v198, v198
	v_exp_f32_e32 v201, v201
	v_exp_f32_e32 v214, v204
	v_exp_f32_e32 v205, v205
	v_exp_f32_e32 v206, v206
	s_waitcnt lgkmcnt(2)
	v_mfma_f32_32x32x16_bf16 v[66:81], v[70:73], v[132:135], 0
	v_exp_f32_e32 v207, v207
	v_exp_f32_e32 v181, v181
	v_exp_f32_e32 v215, v226
	v_exp_f32_e32 v216, v227
	v_exp_f32_e32 v180, v180
	s_waitcnt lgkmcnt(1)
	v_mfma_f32_32x32x16_bf16 v[82:97], v[172:175], v[128:131], v[82:97]
	v_exp_f32_e32 v218, v209
	v_exp_f32_e32 v209, v203
	v_add_f32_e32 v203, 0, v148
	v_add_f32_e32 v203, v163, v203
	v_add_f32_e32 v203, v149, v203
	s_waitcnt lgkmcnt(0)
	v_mfma_f32_32x32x16_bf16 v[66:81], v[228:231], v[128:131], v[66:81]
	v_add_f32_e32 v203, v162, v203
	v_add_f32_e32 v203, v150, v203
	v_add_f32_e32 v203, v161, v203
	v_add_f32_e32 v203, v151, v203
	v_add_f32_e32 v203, v160, v203
	ds_read_b128 v[172:175], v194 offset:32768
	ds_read_b128 v[228:231], v194 offset:40960
	s_waitcnt lgkmcnt(1)
	v_mfma_f32_32x32x16_bf16 v[82:97], v[172:175], v[124:127], v[82:97]
	v_add_f32_e32 v203, v152, v203
	v_add_f32_e32 v203, v159, v203
	v_add_f32_e32 v203, v153, v203
	v_add_f32_e32 v203, v158, v203
	v_exp_f32_e32 v217, v208
	s_waitcnt lgkmcnt(0)
	v_mfma_f32_32x32x16_bf16 v[66:81], v[228:231], v[124:127], v[66:81]
	v_add_f32_e32 v203, v154, v203
	v_add_f32_e32 v203, v157, v203
	v_exp_f32_e32 v219, v223
	v_add_f32_e32 v203, v155, v203
	v_exp_f32_e32 v222, v224
	ds_read_b128 v[172:175], v195 offset:32768
	ds_read_b128 v[228:231], v195 offset:40960
	s_waitcnt lgkmcnt(1)
	v_mfma_f32_32x32x16_bf16 v[82:97], v[172:175], v[120:123], v[82:97]
	v_add_f32_e32 v203, v156, v203
	v_exp_f32_e32 v208, v225
	v_add_f32_e32 v203, v217, v203
	v_add_f32_e32 v203, v218, v203
	v_add_f32_e32 v203, v219, v203
	s_waitcnt lgkmcnt(0)
	v_mfma_f32_32x32x16_bf16 v[66:81], v[228:231], v[120:123], v[66:81]
	v_add_f32_e32 v203, v222, v203
	v_add_f32_e32 v203, v208, v203
	v_add_f32_e32 v203, v198, v203
	v_add_f32_e32 v203, v201, v203
	v_add_f32_e32 v203, v209, v203
	ds_read_b128 v[172:175], v169 offset:32896
	ds_read_b128 v[228:231], v169 offset:41088
	s_waitcnt lgkmcnt(1)
	v_mfma_f32_32x32x16_bf16 v[82:97], v[172:175], v[116:119], v[82:97]
	v_add_f32_e32 v203, v214, v203
	v_add_f32_e32 v203, v205, v203
	v_add_f32_e32 v203, v206, v203
	v_add_f32_e32 v203, v207, v203
	v_add_f32_e32 v203, v181, v203
	s_waitcnt lgkmcnt(0)
	v_mfma_f32_32x32x16_bf16 v[66:81], v[228:231], v[116:119], v[66:81]
	v_add_f32_e32 v203, v215, v203
	v_add_f32_e32 v203, v216, v203
	v_add_f32_e32 v203, v180, v203
	v_mov_b32_e32 v204, v203
	v_cvt_pk_bf16_f32 v148, v148, v163
	ds_read_b128 v[172:175], v193 offset:32896
	ds_read_b128 v[228:231], v193 offset:41088
	s_waitcnt lgkmcnt(1)
	v_mfma_f32_32x32x16_bf16 v[82:97], v[172:175], v[112:115], v[82:97]
	v_cvt_pk_bf16_f32 v149, v149, v162
	v_cvt_pk_bf16_f32 v150, v150, v161
	v_cvt_pk_bf16_f32 v151, v151, v160
	v_cvt_pk_bf16_f32 v152, v152, v159
	v_cvt_pk_bf16_f32 v153, v153, v158
	s_waitcnt lgkmcnt(0)
	v_mfma_f32_32x32x16_bf16 v[66:81], v[228:231], v[112:115], v[66:81]
	v_cvt_pk_bf16_f32 v154, v154, v157
	v_cvt_pk_bf16_f32 v155, v155, v156
	v_cvt_pk_bf16_f32 v156, v217, v218
	v_cvt_pk_bf16_f32 v157, v219, v222
	v_cvt_pk_bf16_f32 v158, v208, v198
	ds_read_b128 v[172:175], v194 offset:32896
	ds_read_b128 v[228:231], v194 offset:41088
	s_waitcnt lgkmcnt(1)
	v_mfma_f32_32x32x16_bf16 v[82:97], v[172:175], v[108:111], v[82:97]
	v_cvt_pk_bf16_f32 v159, v201, v209
	v_cvt_pk_bf16_f32 v160, v214, v205
	v_cvt_pk_bf16_f32 v161, v206, v207
	v_cvt_pk_bf16_f32 v162, v181, v215
	v_cvt_pk_bf16_f32 v163, v216, v180
	s_waitcnt lgkmcnt(0)
	v_mfma_f32_32x32x16_bf16 v[66:81], v[228:231], v[108:111], v[66:81]
	s_nop 1
	v_permlane32_swap_b32_e32 v203, v204
	v_permlane32_swap_b32_e32 v148, v150
	v_permlane32_swap_b32_e32 v149, v151
	v_permlane32_swap_b32_e32 v152, v154
	v_permlane32_swap_b32_e32 v153, v155
	ds_read_b128 v[172:175], v195 offset:32896
	ds_read_b128 v[228:231], v195 offset:41088
	s_waitcnt lgkmcnt(1)
	v_mfma_f32_32x32x16_bf16 v[82:97], v[172:175], v[104:107], v[82:97]
	v_permlane32_swap_b32_e32 v156, v158
	v_permlane32_swap_b32_e32 v157, v159
	v_permlane32_swap_b32_e32 v160, v162
	v_permlane32_swap_b32_e32 v161, v163
	s_waitcnt lgkmcnt(0)
	v_mfma_f32_32x32x16_bf16 v[66:81], v[228:231], v[104:107], v[66:81]
	s_cmp_lt_u32 s3, s2
	s_cselect_b64 s[22:23], -1, 0
	s_cmp_ge_u32 s3, s2
	s_cbranch_scc1 .LBB0_97
	v_add_u32_e32 v242, 0x41, v178
	v_add_u32_e32 v246, 0x61, v178
	v_ashrrev_i32_e32 v243, 31, v242
	v_ashrrev_i32_e32 v247, 31, v246
	v_lshlrev_b64 v[140:141], 8, v[242:243]
	v_lshlrev_b64 v[142:143], 8, v[246:247]
	v_lshl_add_u64 v[242:243], v[170:171], 0, v[140:141]
	v_lshl_add_u64 v[246:247], v[170:171], 0, v[142:143]
	v_lshl_add_u64 v[140:141], v[176:177], 0, v[140:141]
	v_lshl_add_u64 v[144:145], v[176:177], 0, v[142:143]
	global_load_dwordx4 v[242:245], v[242:243], off
	s_nop 0
	global_load_dwordx4 v[246:249], v[246:247], off
	s_nop 0
	global_load_dwordx4 v[140:143], v[140:141], off
	s_nop 0
	global_load_dwordx4 v[144:147], v[144:145], off
	s_mov_b32 s100, 1

; __device__ __forceinline__ void partialSM(f32x16& p0, f32x16& p1, float& m_reg, float& mn, float& alpha, bool rs) {
;     float pmax = p0[0]; for (int r = 1; r < 16; ++r) pmax = fmaxf(pmax, p0[r]); for (int r = 0; r < 16; ++r) pmax = fmaxf(pmax, p1[r]);
;     if (!rs) pmax = -__builtin_inff();
;     { auto rr = __builtin_amdgcn_permlane32_swap(__float_as_uint(pmax), __float_as_uint(pmax), false, false);
;       pmax = fmaxf(__uint_as_float(rr[0]), __uint_as_float(rr[1])); }
;     constexpr float C2 = 1.4426950408889634f * SCALE;
;     if (__builtin_expect(__all((pmax - m_reg) * SCALE <= THR), 1)) { mn = m_reg; alpha = 1.f; }
;     else { mn = fmaxf(m_reg, pmax); alpha = __builtin_amdgcn_exp2f((m_reg - mn) * C2); m_reg = mn; }
.LBB0_99:
	s_add_i32 s0, s3, -1
	s_lshr_b32 s8, s0, 2
	s_cmp_ge_i32 s8, s44
	s_cselect_b64 s[0:1], -1, 0
	s_lshl_b32 s8, 1, s8
	v_and_b32_e32 v148, s8, v165
	v_cmp_ne_u32_e32 vcc, 0, v148
	v_max_f32_e32 v148, v83, v83
	v_max_f32_e32 v149, v82, v82
	v_max_f32_e32 v148, v149, v148
	v_max3_f32 v148, v148, v84, v85
	v_max3_f32 v148, v148, v86, v87
	v_max3_f32 v148, v148, v88, v89
	v_max3_f32 v148, v148, v90, v91
	v_max3_f32 v148, v148, v92, v93
	v_max3_f32 v148, v148, v94, v95
	v_max3_f32 v148, v148, v96, v97
	v_max3_f32 v148, v148, v66, v67
	v_max3_f32 v148, v148, v68, v69
	v_max3_f32 v148, v148, v70, v71
	v_max3_f32 v148, v148, v72, v73
	v_max3_f32 v148, v148, v74, v75
	v_max3_f32 v148, v148, v76, v77
	v_max3_f32 v148, v148, v78, v79
	v_max3_f32 v148, v148, v80, v81
	s_or_b64 s[40:41], s[0:1], vcc
	v_cndmask_b32_e64 v148, v220, v148, s[40:41]
	v_mov_b32_e32 v149, v148
	s_nop 1
	v_permlane32_swap_b32_e32 v148, v149
	v_max_f32_e32 v149, v149, v149
	v_max_f32_e32 v148, v148, v148
	v_max_f32_e32 v148, v148, v149
	v_sub_f32_e32 v149, v148, v179
	v_mul_f32_e32 v149, 0x3db504f3, v149
	v_cmp_ge_f32_e32 vcc, s91, v149
	s_cmp_eq_u64 vcc, exec
	s_cselect_b64 s[42:43], -1, 0
	s_andn2_b64 vcc, exec, s[22:23]
	s_cbranch_vccnz .LBB0_101
	s_waitcnt vmcnt(0)
	s_waitcnt vmcnt(1)
	ds_write_b128 v188, v[140:143] offset:49152
	s_waitcnt vmcnt(0)
	ds_write_b128 v188, v[144:147] offset:57344

; #define SBAR() __builtin_amdgcn_sched_barrier(0)
; #define SLOAD_H(Kp, Vp, k0) do { S.st_v0 = load8(ROW(Vp, k0, sr)); S.st_v1 = load8(ROW(Vp, k0, 32 + sr));              \
;                          S.st_k0 = load8(ROW(Kp, k0, sr)); S.st_k1 = load8(ROW(Kp, k0, 32 + sr)); } while (0)
; __device__ __forceinline__ void moba_block(const BlockRef& cur, const BlockRef& nxt, char* lds, Seam& S) {
;     ...
;     for (int t = 1; t + 1 < NT; t += 2) {
;         HALF_STEP(pB0, pB1, mnB, alB, pA0, pA1, alA, t, 1, 0, 0);
;         HALF_STEP(pA0, pA1, mnA, alA, pB0, pB1, alB, t + 1, 0, 1, 1);
;     }
;     const bool even = (NT & 1) == 0;
;     if (even) { SBAR(); qkt<1>(pB0, pB1, K_lds, r32, hi, S.qr); SBAR(); }
;     SLOAD_H(nxt.K, nxt.V, 0); SBAR();
.LBB0_107:
	s_cmp_eq_u32 s100, 0
	s_cbranch_scc1 .Lmy_exit_nov
	ds_write_b128 v191, v[242:245] offset:16384
	ds_write_b128 v192, v[246:249] offset:16384
